# attention: next-tile K/V loads issued between the two 32-key halves; permlane32_swap row-max exchange; static prio for blocks>=256
# baseline (speedup 1.0000x reference)
; DEV void phase_p3(const Params& p, int l, unsigned char* smem) {
;     ...
;   const int xcd = blockIdx.x & 7;
; #pragma unroll 1
;   for (int qi = 0; qi < 8; ++qi) {
;     const int q = (xcd + qi) & 7;
;     unsigned* qc = (unsigned*)(p.ws + OFF_CNT) + 8 + l * 8 + q;
; #pragma unroll 1
;     for (;;) {
;       __syncthreads();
;       if (tid == 0) s_item = (int)atomicAdd(qc, 1u);
.LBB0_1005:
	v_readlane_b32 s4, v254, 0
	s_nop 3
	s_cmpk_lt_u32 s4, 0x100
	s_cbranch_scc1 .Lattn_prio_skip
	s_setprio 3

; template <int DK, bool PF>
; DEV void attn_item(const u16* __restrict__ qrow, const u16* __restrict__ ka, int ldka, const u16* __restrict__ kb, int ldkb,
;                    const u16* __restrict__ vt, int ldvt, int ntiles, int my_tiles, int kvlen, u16* orow,
;                    unsigned char* smem) {
;     ...
;   auto store_tile = [&]() __attribute__((always_inline)) {
; #pragma unroll
;     for (int i = 0; i < CA; ++i) *(bf16x8*)(lka + i * 8) = rk[i];
; #pragma unroll
;     for (int i = 0; i < 2; ++i) *(bf16x8*)(lkb + i * 8) = rk[CA + i];
; #pragma unroll
;     for (int i = 0; i < 4; ++i) {
;       union { bf16x8 v; uint2 u[2]; } cv;
;       cv.v = rv[i];
;       *(uint2*)(lv + i * 8) = cv.u[0];
;       *(uint2*)(lv + i * 8 + 4) = cv.u[1];
;     }
;   };
;   if (PF) load_tile(0);
; #pragma unroll 1
;   for (int t = 0; t < ntiles; ++t) {
;     __syncthreads();
;     if (!PF) load_tile(t);
;     store_tile();
;     __syncthreads();
;     if (PF && t + 1 < ntiles) load_tile(t + 1);
;     ...
;         union { bf16x8 v[2]; unsigned u[8]; } pfu;
;         float ps = 0.f;
; #pragma unroll
;         for (int r = 0; r < 16; r += 2) {
;           float p0 = __builtin_amdgcn_exp2f(s[r] - mrun);
;           float p1 = __builtin_amdgcn_exp2f(s[r + 1] - mrun);
;           ps += p0 + p1;
;           pfu.u[r >> 1] = pk2bf(p0, p1);
;         }
;         lrun += ps;
; #pragma unroll
;         for (int oc = 0; oc < 2; ++oc)
; #pragma unroll
;           for (int d = 0; d < 4; ++d) o[d] = __builtin_amdgcn_mfma_f32_32x32x16_bf16(vf[oc * 4 + d], pfu.v[oc], o[d], 0, 0, 0);
;       }
.LBB0_1016:
	s_waitcnt vmcnt(29)
	v_add_u32_e32 v64, 0x6400, v214
	s_barrier
	s_waitcnt vmcnt(9)
	ds_write_b128 v212, v[128:131]
	s_waitcnt vmcnt(8)
	ds_write_b128 v212, v[132:135] offset:16
	s_waitcnt vmcnt(7)
	ds_write_b128 v212, v[136:139] offset:32
	s_waitcnt vmcnt(6)
	ds_write_b128 v212, v[140:143] offset:48
	s_waitcnt vmcnt(5)
	ds_write_b128 v218, v[144:147] offset:256
	s_waitcnt vmcnt(4)
	ds_write_b128 v218, v[148:151] offset:272
	s_waitcnt vmcnt(3)
	ds_write2_b64 v64, v[152:153], v[154:155] offset1:1
	v_add_u32_e32 v64, 0x6410, v214
	s_waitcnt vmcnt(2)
	ds_write2_b64 v64, v[156:157], v[158:159] offset1:1
	v_add_u32_e32 v64, 0x6420, v214
	s_add_i32 s96, s8, 1
	s_waitcnt vmcnt(1)
	ds_write2_b64 v64, v[160:161], v[162:163] offset1:1
	v_add_u32_e32 v64, 0x6430, v214
	s_cmp_ge_u32 s96, s12
	s_waitcnt vmcnt(0)
	ds_write2_b64 v64, v[164:165], v[166:167] offset1:1
	s_waitcnt lgkmcnt(0)
	s_barrier
.LBB0_1018:
	v_cmp_lt_i32_e32 vcc, s8, v205
	s_and_saveexec_b64 s[8:9], vcc
	s_cbranch_execz .Lattn_skipload
	v_and_b32_e32 v65, 64, v242
	v_xor_b32_e32 v64, 32, v242
	v_add_u32_e32 v65, 64, v65
	v_cmp_lt_i32_e32 vcc, v64, v65
	s_mov_b32 s13, 0
	s_mov_b64 s[10:11], -1
	v_cndmask_b32_e32 v64, v242, v64, vcc
	v_lshlrev_b32_e32 v220, 2, v64
	s_branch .LBB0_1021
.LBB0_1020:
	v_sub_f32_e32 v64, v64, v219
	v_exp_f32_e32 v223, v64
	v_sub_f32_e32 v64, v65, v219
	v_exp_f32_e32 v227, v64
	v_sub_f32_e32 v64, v66, v219
	v_exp_f32_e32 v222, v64
	v_sub_f32_e32 v64, v67, v219
	v_exp_f32_e32 v226, v64
	v_sub_f32_e32 v64, v68, v219
	v_exp_f32_e32 v229, v64
	v_sub_f32_e32 v64, v69, v219
	v_exp_f32_e32 v69, v64
	v_sub_f32_e32 v64, v70, v219
	v_exp_f32_e32 v228, v64
	v_sub_f32_e32 v64, v71, v219
	v_exp_f32_e32 v68, v64
	v_sub_f32_e32 v70, v72, v219
	v_cvt_pk_bf16_f32 v64, v223, v227
	v_cvt_pk_bf16_f32 v65, v222, v226
	v_cvt_pk_bf16_f32 v66, v229, v69
	v_cvt_pk_bf16_f32 v67, v228, v68
	v_exp_f32_e32 v71, v70
	v_sub_f32_e32 v70, v73, v219
	v_mfma_f32_32x32x16_bf16 v[48:63], v[192:195], v[64:67], v[48:63]
	v_exp_f32_e32 v73, v70
	v_sub_f32_e32 v70, v74, v219
	v_sub_f32_e32 v74, v76, v219
	v_sub_f32_e32 v72, v75, v219
	v_exp_f32_e32 v75, v74
	v_sub_f32_e32 v74, v77, v219
	v_exp_f32_e32 v77, v74
	v_mfma_f32_32x32x16_bf16 v[32:47], v[196:199], v[64:67], v[32:47]
	v_sub_f32_e32 v74, v78, v219
	v_exp_f32_e32 v70, v70
	v_exp_f32_e32 v72, v72
	v_exp_f32_e32 v74, v74
	v_pk_add_f32 v[68:69], v[228:229], v[68:69]
	s_xor_b64 s[10:11], s[10:11], -1
	s_mov_b32 s13, 32
	v_mfma_f32_32x32x16_bf16 v[16:31], v[188:191], v[64:67], v[16:31]
	s_andn2_b64 vcc, exec, s[10:11]
	s_mov_b64 s[10:11], 0
	v_mfma_f32_32x32x16_bf16 v[0:15], v[184:187], v[64:67], v[0:15]
	v_sub_f32_e32 v64, v79, v219
	v_exp_f32_e32 v76, v64
	v_pk_add_f32 v[78:79], v[222:223], v[226:227]
	v_cvt_pk_bf16_f32 v64, v71, v73
	v_cvt_pk_bf16_f32 v65, v70, v72
	v_cvt_pk_bf16_f32 v66, v75, v77
	v_cvt_pk_bf16_f32 v67, v74, v76
	v_pk_add_f32 v[70:71], v[70:71], v[72:73]
	v_pk_add_f32 v[72:73], v[74:75], v[76:77]
	v_add_f32_e32 v74, 0, v79
	v_mfma_f32_32x32x16_bf16 v[48:63], v[176:179], v[64:67], v[48:63]
	v_add_f32_e32 v74, v78, v74
	v_add_f32_e32 v69, v69, v74
	v_add_f32_e32 v68, v68, v69
	v_add_f32_e32 v68, v71, v68
	v_add_f32_e32 v68, v70, v68
	v_add_f32_e32 v68, v73, v68
	v_add_f32_e32 v68, v72, v68
	v_mfma_f32_32x32x16_bf16 v[32:47], v[180:183], v[64:67], v[32:47]
	v_add_f32_e32 v215, v215, v68
	v_mfma_f32_32x32x16_bf16 v[16:31], v[172:175], v[64:67], v[16:31]
	v_mfma_f32_32x32x16_bf16 v[0:15], v[168:171], v[64:67], v[0:15]
	s_cbranch_vccz .LBB0_1023
	s_cmp_ge_u32 s96, s12
	s_cbranch_scc1 .LBB0_1021
	s_lshl_b64 s[10:11], s[96:97], 17
	v_lshl_add_u64 v[64:65], v[206:207], 0, s[10:11]
	s_lshl_b64 s[10:11], s[96:97], 13
	global_load_dwordx4 v[128:131], v[64:65], off
	global_load_dwordx4 v[132:135], v[64:65], off offset:16
	global_load_dwordx4 v[136:139], v[64:65], off offset:32
	global_load_dwordx4 v[140:143], v[64:65], off offset:48
	v_lshl_add_u64 v[64:65], v[208:209], 0, s[10:11]
	s_lshl_b64 s[10:11], s[96:97], 7
	global_load_dwordx4 v[144:147], v[64:65], off
	global_load_dwordx4 v[148:151], v[64:65], off offset:16
	v_lshl_add_u64 v[64:65], v[210:211], 0, s[10:11]
	global_load_dwordx4 v[152:155], v[64:65], off
	global_load_dwordx4 v[156:159], v[64:65], off offset:16
	global_load_dwordx4 v[160:163], v[64:65], off offset:32
	global_load_dwordx4 v[164:167], v[64:65], off offset:48
	s_mov_b64 s[10:11], 0
; template <int DK, bool PF>
; DEV void attn_item(const u16* __restrict__ qrow, const u16* __restrict__ ka, int ldka, const u16* __restrict__ kb, int ldkb,
;                    const u16* __restrict__ vt, int ldvt, int ntiles, int my_tiles, int kvlen, u16* orow,
;                    unsigned char* smem) {
;     ...
;         const u16* kp = sK + (mi * 32 + l31) * KST + hh * 8;
;         constexpr int KB = QREG ? 12 : 4;
; #pragma unroll
;         for (int k0 = 0; k0 < DK / 16; k0 += KB) {
;           bf16x8 kf[KB];
; #pragma unroll
;           for (int i = 0; i < KB; ++i) kf[i] = *(const bf16x8*)(kp + (k0 + i) * 16);
;           __builtin_amdgcn_sched_barrier(0);
; #pragma unroll
;           for (int i = 0; i < KB; ++i) {
;             bf16x8 qv;
;             if (QREG) qv = qf[k0 + i];
;             else qv = *(const bf16x8*)(qp + (k0 + i) * 16);
;             s = __builtin_amdgcn_mfma_f32_32x32x16_bf16(kf[i], qv, s, 0, 0, 0);
;           }
;         }
;         bf16x8 vf[8];
;         {
;           const u16* vp = sV + l31 * VST + mi * 32 + 4 * hh;
; #pragma unroll
;           for (int oc = 0; oc < 2; ++oc)
; #pragma unroll
;             for (int d = 0; d < 4; ++d) {
;               union { bf16x8 v; uint2 u[2]; } cv;
;               cv.u[0] = *(const uint2*)(vp + d * 32 * VST + oc * 16);
;               cv.u[1] = *(const uint2*)(vp + d * 32 * VST + oc * 16 + 8);
;               vf[oc * 4 + d] = cv.v;
;             }
;           __builtin_amdgcn_sched_barrier(0);
;         }
;         if (key0 + 64 > kvlen) {
; #pragma unroll
;           for (int r = 0; r < 16; ++r) {
;             int key = key0 + mi * 32 + (r & 3) + 8 * (r >> 2) + 4 * hh;
;             if (key >= kvlen) s[r] = -1e30f;
;           }
;         }
;         float mx = -1e30f;
; #pragma unroll
;         for (int r = 0; r < 16; ++r) mx = fmaxf(mx, s[r]);
;         mx = fmaxf(mx, __shfl_xor(mx, 32, 64));
;         if (__builtin_amdgcn_ballot_w64(mx > mrun) != 0ull) {
;           const float mnew = fmaxf(mrun, mx);
;           const float alpha = __builtin_amdgcn_exp2f(mrun - mnew);
;           mrun = mnew;
;           lrun *= alpha;
; #pragma unroll
;           for (int d = 0; d < 4; ++d)
; #pragma unroll
;             for (int r = 0; r < 16; ++r) o[d][r] *= alpha;
;         }
.LBB0_1021:
	v_or_b32_e32 v64, s13, v217
	v_mad_u32_u24 v68, v64, s54, v224
	ds_read_b128 v[64:67], v68
	ds_read_b128 v[168:171], v68 offset:32
	ds_read_b128 v[172:175], v68 offset:64
	ds_read_b128 v[176:179], v68 offset:96
	ds_read_b128 v[180:183], v68 offset:128
	ds_read_b128 v[184:187], v68 offset:160
	ds_read_b128 v[188:191], v68 offset:192
	ds_read_b128 v[192:195], v68 offset:224
	ds_read_b128 v[196:199], v68 offset:256
	ds_read_b128 v[226:229], v68 offset:288
	ds_read_b128 v[248:251], v68 offset:320
	ds_read_b128 v[234:237], v68 offset:352
	s_waitcnt lgkmcnt(11)
	v_mfma_f32_32x32x16_bf16 v[64:79], v[64:67], v[80:83], 0
	s_waitcnt lgkmcnt(10)
	v_mfma_f32_32x32x16_bf16 v[64:79], v[168:171], v[84:87], v[64:79]
	v_lshl_add_u32 v168, s13, 1, v213
	v_add_u32_e32 v169, 0x6000, v168
	v_add_u32_e32 v170, 0x8000, v168
	s_waitcnt lgkmcnt(9)
	v_mfma_f32_32x32x16_bf16 v[64:79], v[172:175], v[88:91], v[64:79]
	s_waitcnt lgkmcnt(8)
	v_mfma_f32_32x32x16_bf16 v[64:79], v[176:179], v[92:95], v[64:79]
	s_waitcnt lgkmcnt(7)
	v_mfma_f32_32x32x16_bf16 v[64:79], v[180:183], v[96:99], v[64:79]
	s_waitcnt lgkmcnt(6)
	v_mfma_f32_32x32x16_bf16 v[64:79], v[184:187], v[100:103], v[64:79]
	s_waitcnt lgkmcnt(5)
	v_mfma_f32_32x32x16_bf16 v[64:79], v[188:191], v[104:107], v[64:79]
	s_waitcnt lgkmcnt(4)
	v_mfma_f32_32x32x16_bf16 v[64:79], v[192:195], v[108:111], v[64:79]
	ds_read2_b64 v[192:195], v169 offset0:128 offset1:130
	ds_read2_b64 v[176:179], v169 offset0:132 offset1:134
	v_add_u32_e32 v169, 0x7000, v168
	v_add_u32_e32 v168, 0x9000, v168
	ds_read2_b64 v[188:191], v170 offset0:192 offset1:194
	s_waitcnt lgkmcnt(6)
	v_mfma_f32_32x32x16_bf16 v[64:79], v[196:199], v[112:115], v[64:79]
	ds_read2_b64 v[196:199], v169 offset0:160 offset1:162
	ds_read2_b64 v[184:187], v168 offset0:224 offset1:226
	ds_read2_b64 v[180:183], v169 offset0:164 offset1:166
	ds_read2_b64 v[172:175], v170 offset0:196 offset1:198
	ds_read2_b64 v[168:171], v168 offset0:228 offset1:230
	s_waitcnt lgkmcnt(10)
	v_mfma_f32_32x32x16_bf16 v[64:79], v[226:229], v[116:119], v[64:79]
	s_waitcnt lgkmcnt(9)
	v_mfma_f32_32x32x16_bf16 v[64:79], v[248:251], v[120:123], v[64:79]
	s_waitcnt lgkmcnt(8)
	v_mfma_f32_32x32x16_bf16 v[64:79], v[234:237], v[124:127], v[64:79]
	s_nop 11
	v_max3_f32 v221, v64, s53, v65
	v_max3_f32 v221, v221, v66, v67
	v_max3_f32 v221, v221, v68, v69
	v_max3_f32 v221, v221, v70, v71
	v_max3_f32 v221, v221, v72, v73
	v_max3_f32 v221, v221, v74, v75
	v_max3_f32 v221, v221, v76, v77
	v_max3_f32 v221, v221, v78, v79
	v_mov_b32_e32 v222, v221
	s_nop 1
	v_permlane32_swap_b32_e32 v222, v221
	s_waitcnt lgkmcnt(0)
	v_max_f32_e32 v221, v221, v222
	v_cmp_gt_f32_e32 vcc, v221, v219
	s_cbranch_vccz .LBB0_1020
	v_max_f32_e32 v221, v221, v221
	v_max_f32_e32 v222, v219, v219
	v_max_f32_e32 v221, v222, v221
	v_sub_f32_e32 v219, v219, v221
	v_exp_f32_e32 v222, v219
	v_mov_b32_e32 v219, v221
	v_pk_mul_f32 v[62:63], v[62:63], v[222:223] op_sel_hi:[1,0]
	v_pk_mul_f32 v[60:61], v[60:61], v[222:223] op_sel_hi:[1,0]
	v_pk_mul_f32 v[58:59], v[58:59], v[222:223] op_sel_hi:[1,0]
	v_pk_mul_f32 v[56:57], v[56:57], v[222:223] op_sel_hi:[1,0]
	v_pk_mul_f32 v[54:55], v[54:55], v[222:223] op_sel_hi:[1,0]
	v_pk_mul_f32 v[52:53], v[52:53], v[222:223] op_sel_hi:[1,0]
	v_pk_mul_f32 v[50:51], v[50:51], v[222:223] op_sel_hi:[1,0]
	v_pk_mul_f32 v[48:49], v[48:49], v[222:223] op_sel_hi:[1,0]
	v_pk_mul_f32 v[46:47], v[46:47], v[222:223] op_sel_hi:[1,0]
	v_pk_mul_f32 v[44:45], v[44:45], v[222:223] op_sel_hi:[1,0]
	v_pk_mul_f32 v[42:43], v[42:43], v[222:223] op_sel_hi:[1,0]
	v_pk_mul_f32 v[40:41], v[40:41], v[222:223] op_sel_hi:[1,0]
	v_pk_mul_f32 v[38:39], v[38:39], v[222:223] op_sel_hi:[1,0]
	v_pk_mul_f32 v[36:37], v[36:37], v[222:223] op_sel_hi:[1,0]
	v_pk_mul_f32 v[34:35], v[34:35], v[222:223] op_sel_hi:[1,0]
	v_pk_mul_f32 v[32:33], v[32:33], v[222:223] op_sel_hi:[1,0]
	v_pk_mul_f32 v[30:31], v[30:31], v[222:223] op_sel_hi:[1,0]
	v_pk_mul_f32 v[28:29], v[28:29], v[222:223] op_sel_hi:[1,0]
	v_pk_mul_f32 v[26:27], v[26:27], v[222:223] op_sel_hi:[1,0]
	v_pk_mul_f32 v[24:25], v[24:25], v[222:223] op_sel_hi:[1,0]
	v_pk_mul_f32 v[22:23], v[22:23], v[222:223] op_sel_hi:[1,0]
	v_pk_mul_f32 v[20:21], v[20:21], v[222:223] op_sel_hi:[1,0]
	v_pk_mul_f32 v[18:19], v[18:19], v[222:223] op_sel_hi:[1,0]
	v_pk_mul_f32 v[16:17], v[16:17], v[222:223] op_sel_hi:[1,0]
	v_pk_mul_f32 v[14:15], v[14:15], v[222:223] op_sel_hi:[1,0]
	v_pk_mul_f32 v[12:13], v[12:13], v[222:223] op_sel_hi:[1,0]
	v_pk_mul_f32 v[10:11], v[10:11], v[222:223] op_sel_hi:[1,0]
	v_pk_mul_f32 v[8:9], v[8:9], v[222:223] op_sel_hi:[1,0]
	v_pk_mul_f32 v[6:7], v[6:7], v[222:223] op_sel_hi:[1,0]
	v_pk_mul_f32 v[4:5], v[4:5], v[222:223] op_sel_hi:[1,0]
	v_pk_mul_f32 v[2:3], v[2:3], v[222:223] op_sel_hi:[1,0]
	v_pk_mul_f32 v[0:1], v[0:1], v[222:223] op_sel_hi:[1,0]
	v_mul_f32_e32 v215, v215, v222
	s_branch .LBB0_1020

; template <int DK, bool PF>
; DEV void attn_item(const u16* __restrict__ qrow, const u16* __restrict__ ka, int ldka, const u16* __restrict__ kb, int ldkb,
;                    const u16* __restrict__ vt, int ldvt, int ntiles, int my_tiles, int kvlen, u16* orow,
;                    unsigned char* smem) {
;     ...
;     if (PF && t + 1 < ntiles) load_tile(t + 1);
;     if (t < my_tiles) {
; DEV void phase_p3(const Params& p, int l, unsigned char* smem) {
;     ...
; #pragma unroll 1
;   for (int it = blockIdx.x; it < 512; it += gridDim.x) lru_item(p, l, 16 + (it >> 4), (it >> 1) & 7, it & 1, smem);
.Lattn_skipload:
	s_or_b64 exec, exec, s[8:9]
	s_cmp_ge_u32 s96, s12
	s_cbranch_scc1 .LBB0_1023
	s_lshl_b64 s[10:11], s[96:97], 17
	v_lshl_add_u64 v[64:65], v[206:207], 0, s[10:11]
	s_lshl_b64 s[10:11], s[96:97], 13
	global_load_dwordx4 v[128:131], v[64:65], off
	global_load_dwordx4 v[132:135], v[64:65], off offset:16
	global_load_dwordx4 v[136:139], v[64:65], off offset:32
	global_load_dwordx4 v[140:143], v[64:65], off offset:48
	v_lshl_add_u64 v[64:65], v[208:209], 0, s[10:11]
	s_lshl_b64 s[10:11], s[96:97], 7
	global_load_dwordx4 v[144:147], v[64:65], off
	global_load_dwordx4 v[148:151], v[64:65], off offset:16
	v_lshl_add_u64 v[64:65], v[210:211], 0, s[10:11]
	global_load_dwordx4 v[152:155], v[64:65], off
	global_load_dwordx4 v[156:159], v[64:65], off offset:16
	global_load_dwordx4 v[160:163], v[64:65], off offset:32
	global_load_dwordx4 v[164:167], v[64:65], off offset:48
	s_branch .LBB0_1023
.LBB0_1025:
	s_setprio 0
	v_readlane_b32 s0, v254, 56
	v_readlane_b32 s1, v254, 57
	s_andn2_b64 vcc, exec, s[0:1]
	s_cbranch_vccnz .LBB0_1157
	v_readlane_b32 s12, v255, 26
	v_readlane_b32 s13, v255, 27
	s_mov_b32 s13, s97
	s_lshl_b64 s[0:1], s[12:13], 14
	s_lshl_b32 s16, s12, 10
	s_lshl_b64 s[4:5], s[12:13], 17
	s_add_u32 s17, s14, 0x8100000
	s_addc_u32 s21, s15, 0
	s_add_u32 s36, s14, 0x10200000
	s_addc_u32 s37, s15, 0
	s_add_u32 s6, s14, s20
	s_addc_u32 s7, s15, 0
	v_readlane_b32 s8, v254, 63
	v_readlane_b32 s9, v255, 0
	s_add_u32 s20, s8, s0
	s_addc_u32 s38, s9, s1
	s_add_u32 s39, s30, s4
	s_addc_u32 s55, s31, s5
	s_add_u32 s56, s6, 0x3b6b0100
	s_addc_u32 s57, s7, 0
	v_readlane_b32 s10, v255, 1
	v_readlane_b32 s11, v255, 2
	s_add_u32 s58, s6, 0x3b6f0100
	v_writelane_b32 v255, s12, 26
	s_addc_u32 s59, s7, 0
	s_lshl_b32 s60, s12, 5
	v_writelane_b32 v255, s13, 27
	v_readlane_b32 s61, v254, 0
	s_branch .LBB0_1028

; template <int MI>
; DEV void gemm_mm(f32x16 (&acc)[MI][2], const u16* __restrict__ A, int lda, const u16* __restrict__ B, int ldb, int K,
;                  unsigned char* smem) {
;   constexpr int BM = MI * 64;
;   u16* sA = (u16*)smem;
;   u16* sB = sA + BM * LDT;
;   const int tid = TIDX(), lane = tid & 63, w = tid >> 6, wm = w >> 1, wn = w & 1;
;   const int srow = tid >> 3, scol = (tid & 7) * 8;
;   const u16* ap = A + (size_t)srow * lda + scol;
;   const u16* bp = B + (size_t)srow * ldb + scol;
;   bf16x8 ra[MI * 2], rb[4];
; #pragma unroll
;   for (int i = 0; i < MI * 2; ++i) ra[i] = *(const bf16x8*)(ap + (size_t)(32 * i) * lda);
; #pragma unroll
;   for (int i = 0; i < 4; ++i) rb[i] = *(const bf16x8*)(bp + (size_t)(32 * i) * ldb);
;   const int nk = K >> 6;
;   const int fro = (lane & 31) * LDT + (lane >> 5) * 8;
; template <int MI>
; DEV void zero_acc_t(f32x16 (&acc)[MI][2]) {
; #pragma unroll
;   for (int a = 0; a < MI; ++a)
; #pragma unroll
;     for (int b = 0; b < 2; ++b)
; #pragma unroll
;       for (int r = 0; r < 16; ++r) acc[a][b][r] = 0.f;
; }
.LBB0_1374:
	s_lshl_b32 s0, s4, 5
	s_and_b32 s14, s0, 0xffffff00
	s_ashr_i32 s15, s14, 31
	v_mov_b32_e32 v8, v232
	s_and_b32 s13, s4, 7
	s_lshl_b64 s[0:1], s[14:15], 10
	s_lshl_b64 s[14:15], s[14:15], 11
	s_add_u32 s14, s7, s14
	v_ashrrev_i32_e32 v0, 3, v8
	v_ashrrev_i32_e32 v1, 31, v0
	s_addc_u32 s15, s8, s15
	v_lshlrev_b64 v[2:3], 11, v[0:1]
	v_lshlrev_b32_e32 v1, 4, v8
	v_lshl_add_u64 v[4:5], s[14:15], 0, v[2:3]
	v_and_b32_e32 v224, 0x70, v1
	v_lshl_add_u64 v[176:177], v[4:5], 0, v[224:225]
	v_add_co_u32_e32 v4, vcc, s35, v176
	s_lshl_b32 s16, s13, 18
	s_nop 0
	v_addc_co_u32_e32 v5, vcc, 0, v177, vcc
	v_add_co_u32_e32 v6, vcc, s33, v176
	s_add_u32 s16, s9, s16
	s_nop 0
	v_addc_co_u32_e32 v7, vcc, 0, v177, vcc
	global_load_dwordx4 v[128:131], v[4:5], off
	global_load_dwordx4 v[132:135], v[6:7], off
	v_add_co_u32_e32 v4, vcc, s40, v176
	s_addc_u32 s17, s10, 0
	s_nop 0
	v_addc_co_u32_e32 v5, vcc, 0, v177, vcc
	v_add_co_u32_e32 v6, vcc, s60, v176
	v_lshl_add_u64 v[2:3], s[16:17], 0, v[2:3]
	s_nop 0
	v_addc_co_u32_e32 v7, vcc, 0, v177, vcc
	global_load_dwordx4 v[140:143], v[4:5], off
	global_load_dwordx4 v[144:147], v[6:7], off
	v_add_co_u32_e32 v4, vcc, s61, v176
	v_lshl_add_u64 v[178:179], v[2:3], 0, v[224:225]
	s_nop 0
	v_addc_co_u32_e32 v5, vcc, 0, v177, vcc
	v_add_co_u32_e32 v6, vcc, s3, v176
	v_and_b32_e32 v1, 64, v8
	s_nop 0
	v_addc_co_u32_e32 v7, vcc, 0, v177, vcc
	global_load_dwordx4 v[148:151], v[4:5], off
	global_load_dwordx4 v[152:155], v[6:7], off
	v_add_co_u32_e32 v4, vcc, s2, v176
	global_load_dwordx4 v[136:139], v[176:177], off
	global_load_dwordx4 v[156:159], v[178:179], off
	v_addc_co_u32_e32 v5, vcc, 0, v177, vcc
	v_add_co_u32_e32 v2, vcc, s35, v178
	v_mul_u32_u24_e32 v1, 0x90, v1
	s_nop 0
	v_addc_co_u32_e32 v3, vcc, 0, v179, vcc
	global_load_dwordx4 v[160:163], v[4:5], off
	global_load_dwordx4 v[164:167], v[2:3], off
	v_add_co_u32_e32 v2, vcc, s33, v178
	s_mov_b32 s14, 16
	s_nop 0
	v_addc_co_u32_e32 v3, vcc, 0, v179, vcc
	v_add_co_u32_e32 v4, vcc, s40, v178
	s_nop 1
	v_addc_co_u32_e32 v5, vcc, 0, v179, vcc
	global_load_dwordx4 v[168:171], v[2:3], off
	global_load_dwordx4 v[172:175], v[4:5], off
	v_and_b32_e32 v2, 31, v8
	v_lshrrev_b32_e32 v3, 2, v8
	v_mul_u32_u24_e32 v2, 0x48, v2
	v_and_b32_e32 v3, 8, v3
	v_and_b32_e32 v4, 0xfffff80, v8
	v_add_lshl_u32 v2, v2, v3, 1
	v_mul_lo_u32 v3, v0, s49
	v_mul_lo_u32 v4, v4, s49
	v_mov_b32_e32 v0, 0
	v_add_u32_e32 v180, v224, v3
	v_add_u32_e32 v181, v2, v4
	v_add_u32_e32 v182, v2, v1
	v_mov_b32_e32 v1, v0
	v_mov_b32_e32 v2, v0
	v_mov_b32_e32 v3, v0
	v_mov_b32_e32 v4, v0
	v_mov_b32_e32 v5, v0
	v_mov_b32_e32 v6, v0
	v_mov_b32_e32 v7, v0
	v_mov_b32_e32 v8, v0
	v_mov_b32_e32 v9, v0
	v_mov_b32_e32 v10, v0
	v_mov_b32_e32 v11, v0
	v_mov_b32_e32 v12, v0
	v_mov_b32_e32 v13, v0
	v_mov_b32_e32 v14, v0
	v_mov_b32_e32 v15, v0
	v_mov_b32_e32 v16, v0
	v_mov_b32_e32 v17, v0
	v_mov_b32_e32 v18, v0
	v_mov_b32_e32 v19, v0
	v_mov_b32_e32 v20, v0
	v_mov_b32_e32 v21, v0
	v_mov_b32_e32 v22, v0
	v_mov_b32_e32 v23, v0
	v_mov_b32_e32 v24, v0
	v_mov_b32_e32 v25, v0
	v_mov_b32_e32 v26, v0
	v_mov_b32_e32 v27, v0
	v_mov_b32_e32 v28, v0
	v_mov_b32_e32 v29, v0
	v_mov_b32_e32 v30, v0
	v_mov_b32_e32 v31, v0
	v_mov_b32_e32 v32, v0
	v_mov_b32_e32 v33, v0
	v_mov_b32_e32 v34, v0
	v_mov_b32_e32 v35, v0
	v_mov_b32_e32 v36, v0
	v_mov_b32_e32 v37, v0
	v_mov_b32_e32 v38, v0
	v_mov_b32_e32 v39, v0
	v_mov_b32_e32 v40, v0
	v_mov_b32_e32 v41, v0
	v_mov_b32_e32 v42, v0
	v_mov_b32_e32 v43, v0
	v_mov_b32_e32 v44, v0
	v_mov_b32_e32 v45, v0
	v_mov_b32_e32 v46, v0
	v_mov_b32_e32 v47, v0
	v_mov_b32_e32 v48, v0
	v_mov_b32_e32 v49, v0
	v_mov_b32_e32 v50, v0
	v_mov_b32_e32 v51, v0
	v_mov_b32_e32 v52, v0
	v_mov_b32_e32 v53, v0
	v_mov_b32_e32 v54, v0
	v_mov_b32_e32 v55, v0
	v_mov_b32_e32 v56, v0
	v_mov_b32_e32 v57, v0
	v_mov_b32_e32 v58, v0
	v_mov_b32_e32 v59, v0
	v_mov_b32_e32 v60, v0
	v_mov_b32_e32 v61, v0
	v_mov_b32_e32 v62, v0
	v_mov_b32_e32 v63, v0
	s_waitcnt vmcnt(19)
	v_mov_b32_e32 v64, v0
	v_mov_b32_e32 v65, v0
	v_mov_b32_e32 v66, v0
	v_mov_b32_e32 v67, v0
	s_waitcnt vmcnt(18)
	v_mov_b32_e32 v68, v0
	v_mov_b32_e32 v69, v0
	v_mov_b32_e32 v70, v0
	v_mov_b32_e32 v71, v0
	s_waitcnt vmcnt(17)
	v_mov_b32_e32 v72, v0
	v_mov_b32_e32 v73, v0
	v_mov_b32_e32 v74, v0
	v_mov_b32_e32 v75, v0
	s_waitcnt vmcnt(15)
	v_mov_b32_e32 v76, v0
	v_mov_b32_e32 v77, v0
	v_mov_b32_e32 v78, v0
	v_mov_b32_e32 v79, v0
	v_mov_b32_e32 v80, v0
	v_mov_b32_e32 v81, v0
	v_mov_b32_e32 v82, v0
	v_mov_b32_e32 v83, v0
	s_waitcnt vmcnt(14)
	v_mov_b32_e32 v84, v0
	v_mov_b32_e32 v85, v0
	v_mov_b32_e32 v86, v0
	v_mov_b32_e32 v87, v0
	s_waitcnt vmcnt(13)
	v_mov_b32_e32 v88, v0
	v_mov_b32_e32 v89, v0
	v_mov_b32_e32 v90, v0
	v_mov_b32_e32 v91, v0
	s_waitcnt vmcnt(12)
	v_mov_b32_e32 v92, v0
	v_mov_b32_e32 v93, v0
	v_mov_b32_e32 v94, v0
	v_mov_b32_e32 v95, v0
	v_mov_b32_e32 v96, v0
	v_mov_b32_e32 v97, v0
	v_mov_b32_e32 v98, v0
	v_mov_b32_e32 v99, v0
	v_mov_b32_e32 v100, v0
	v_mov_b32_e32 v101, v0
	v_mov_b32_e32 v102, v0
	v_mov_b32_e32 v103, v0
	v_mov_b32_e32 v104, v0
	v_mov_b32_e32 v105, v0
	v_mov_b32_e32 v106, v0
	v_mov_b32_e32 v107, v0
	v_mov_b32_e32 v108, v0
	v_mov_b32_e32 v109, v0
	v_mov_b32_e32 v110, v0
	v_mov_b32_e32 v111, v0
	v_mov_b32_e32 v112, v0
	v_mov_b32_e32 v113, v0
	v_mov_b32_e32 v114, v0
	v_mov_b32_e32 v115, v0
	v_mov_b32_e32 v116, v0
	v_mov_b32_e32 v117, v0
	v_mov_b32_e32 v118, v0
	v_mov_b32_e32 v119, v0
	v_mov_b32_e32 v120, v0
	v_mov_b32_e32 v121, v0
	v_mov_b32_e32 v122, v0
	v_mov_b32_e32 v123, v0
	v_mov_b32_e32 v124, v0
	v_mov_b32_e32 v125, v0
	v_mov_b32_e32 v126, v0
	v_mov_b32_e32 v127, v0
	s_branch .LBB0_1376
; template <int MI>
; DEV void gemm_mm(f32x16 (&acc)[MI][2], const u16* __restrict__ A, int lda, const u16* __restrict__ B, int ldb, int K,
;                  unsigned char* smem) {
;     ...
;   for (int kt = 0; kt < nk; ++kt) {
;     __syncthreads();
; #pragma unroll
;     for (int i = 0; i < MI * 2; ++i) *(bf16x8*)(sA + (srow + 32 * i) * LDT + scol) = ra[i];
; #pragma unroll
;     for (int i = 0; i < 4; ++i) *(bf16x8*)(sB + (srow + 32 * i) * LDT + scol) = rb[i];
;     __syncthreads();
;     if (kt + 1 < nk) {
;       ap += 64;
;       bp += 64;
; #pragma unroll
;       for (int i = 0; i < MI * 2; ++i) ra[i] = *(const bf16x8*)(ap + (size_t)(32 * i) * lda);
; #pragma unroll
;       for (int i = 0; i < 4; ++i) rb[i] = *(const bf16x8*)(bp + (size_t)(32 * i) * ldb);
;     }
;     bf16x8 af[2][MI], bfr[2][2];
; #pragma unroll
;     for (int i = 0; i < MI; ++i) af[0][i] = *(const bf16x8*)(sA + (wm * (MI * 32) + i * 32) * LDT + fro);
; #pragma unroll
;     for (int i = 0; i < 2; ++i) bfr[0][i] = *(const bf16x8*)(sB + (wn * 64 + i * 32) * LDT + fro);
; #pragma unroll
;     for (int ks = 0; ks < 4; ++ks) {
;       if (ks + 1 < 4) {
; #pragma unroll
;         for (int i = 0; i < MI; ++i)
;           af[(ks + 1) & 1][i] = *(const bf16x8*)(sA + (wm * (MI * 32) + i * 32) * LDT + fro + (ks + 1) * 16);
; #pragma unroll
;         for (int i = 0; i < 2; ++i)
;           bfr[(ks + 1) & 1][i] = *(const bf16x8*)(sB + (wn * 64 + i * 32) * LDT + fro + (ks + 1) * 16);
;       }
;       __builtin_amdgcn_sched_barrier(0);
;       __builtin_amdgcn_s_setprio(1);
; #pragma unroll
;       for (int mi = 0; mi < MI; ++mi)
; #pragma unroll
;         for (int ni = 0; ni < 2; ++ni)
;           acc[mi][ni] = __builtin_amdgcn_mfma_f32_32x32x16_bf16(af[ks & 1][mi], bfr[ks & 1][ni], acc[mi][ni], 0, 0, 0);
;       __builtin_amdgcn_s_setprio(0);
;       __builtin_amdgcn_sched_barrier(0);
;     }
.LBB0_1375:
	ds_read_b128 v[184:187], v181
	ds_read_b128 v[188:191], v181 offset:32
	ds_read_b128 v[192:195], v181 offset:4608
	ds_read_b128 v[196:199], v181 offset:4640
	ds_read_b128 v[200:203], v181 offset:9216
	ds_read_b128 v[204:207], v181 offset:9248
	ds_read_b128 v[208:211], v181 offset:13824
	ds_read_b128 v[212:215], v181 offset:13856
	ds_read_b128 v[216:219], v182 offset:36864
	ds_read_b128 v[220:223], v182 offset:36896
	ds_read_b128 v[226:229], v182 offset:41472
	ds_read_b128 v[234:237], v182 offset:41504
	s_setprio 1
	s_waitcnt lgkmcnt(3)
	v_mfma_f32_32x32x16_bf16 v[112:127], v[184:187], v[216:219], v[112:127]
	s_waitcnt lgkmcnt(1)
	v_mfma_f32_32x32x16_bf16 v[96:111], v[184:187], v[226:229], v[96:111]
	v_mfma_f32_32x32x16_bf16 v[80:95], v[192:195], v[216:219], v[80:95]
	v_mfma_f32_32x32x16_bf16 v[64:79], v[192:195], v[226:229], v[64:79]
	v_mfma_f32_32x32x16_bf16 v[48:63], v[200:203], v[216:219], v[48:63]
	v_mfma_f32_32x32x16_bf16 v[32:47], v[200:203], v[226:229], v[32:47]
	v_mfma_f32_32x32x16_bf16 v[16:31], v[208:211], v[216:219], v[16:31]
	v_mfma_f32_32x32x16_bf16 v[0:15], v[208:211], v[226:229], v[0:15]
	s_setprio 0
	ds_read_b128 v[184:187], v181 offset:64
	ds_read_b128 v[192:195], v181 offset:4672
	ds_read_b128 v[200:203], v181 offset:9280
	ds_read_b128 v[208:211], v181 offset:13888
	ds_read_b128 v[216:219], v182 offset:36928
	ds_read_b128 v[226:229], v182 offset:41536
	s_setprio 1
	v_mfma_f32_32x32x16_bf16 v[112:127], v[188:191], v[220:223], v[112:127]
	s_waitcnt lgkmcnt(6)
	v_mfma_f32_32x32x16_bf16 v[96:111], v[188:191], v[234:237], v[96:111]
	v_mfma_f32_32x32x16_bf16 v[80:95], v[196:199], v[220:223], v[80:95]
	v_mfma_f32_32x32x16_bf16 v[64:79], v[196:199], v[234:237], v[64:79]
	v_mfma_f32_32x32x16_bf16 v[48:63], v[204:207], v[220:223], v[48:63]
	v_mfma_f32_32x32x16_bf16 v[32:47], v[204:207], v[234:237], v[32:47]
	v_mfma_f32_32x32x16_bf16 v[16:31], v[212:215], v[220:223], v[16:31]
	v_mfma_f32_32x32x16_bf16 v[0:15], v[212:215], v[234:237], v[0:15]
	s_setprio 0
	ds_read_b128 v[188:191], v181 offset:96
	ds_read_b128 v[196:199], v181 offset:4704
	ds_read_b128 v[204:207], v181 offset:9312
	ds_read_b128 v[212:215], v181 offset:13920
	ds_read_b128 v[220:223], v182 offset:36960
	ds_read_b128 v[234:237], v182 offset:41568
	s_setprio 1
	s_waitcnt lgkmcnt(7)
	v_mfma_f32_32x32x16_bf16 v[112:127], v[184:187], v[216:219], v[112:127]
	s_waitcnt lgkmcnt(6)
	v_mfma_f32_32x32x16_bf16 v[96:111], v[184:187], v[226:229], v[96:111]
	v_mfma_f32_32x32x16_bf16 v[80:95], v[192:195], v[216:219], v[80:95]
	v_mfma_f32_32x32x16_bf16 v[64:79], v[192:195], v[226:229], v[64:79]
	v_mfma_f32_32x32x16_bf16 v[48:63], v[200:203], v[216:219], v[48:63]
	v_mfma_f32_32x32x16_bf16 v[32:47], v[200:203], v[226:229], v[32:47]
	v_mfma_f32_32x32x16_bf16 v[16:31], v[208:211], v[216:219], v[16:31]
	v_mfma_f32_32x32x16_bf16 v[0:15], v[208:211], v[226:229], v[0:15]
	s_setprio 0
	s_setprio 1
	s_waitcnt lgkmcnt(1)
	v_mfma_f32_32x32x16_bf16 v[112:127], v[188:191], v[220:223], v[112:127]
	s_waitcnt lgkmcnt(0)
	v_mfma_f32_32x32x16_bf16 v[96:111], v[188:191], v[234:237], v[96:111]
	v_mfma_f32_32x32x16_bf16 v[80:95], v[196:199], v[220:223], v[80:95]
	v_mfma_f32_32x32x16_bf16 v[64:79], v[196:199], v[234:237], v[64:79]
	v_mfma_f32_32x32x16_bf16 v[48:63], v[204:207], v[220:223], v[48:63]
	v_mfma_f32_32x32x16_bf16 v[32:47], v[204:207], v[234:237], v[32:47]
	v_mfma_f32_32x32x16_bf16 v[16:31], v[212:215], v[220:223], v[16:31]
	v_mfma_f32_32x32x16_bf16 v[0:15], v[212:215], v[234:237], v[0:15]
	s_setprio 0
	s_add_i32 s14, s14, -1
	s_cmp_lg_u32 s14, 0
	s_cbranch_scc0 .LBB0_1373
.LBB0_1376:
	s_cmp_eq_u32 s14, 1
	s_barrier
	s_waitcnt vmcnt(5)
	ds_write_b128 v180, v[136:139]
	ds_write_b128 v180, v[128:131] offset:4608
	ds_write_b128 v180, v[132:135] offset:9216
	ds_write_b128 v180, v[140:143] offset:13824
	ds_write_b128 v180, v[144:147] offset:18432
	ds_write_b128 v180, v[148:151] offset:23040
	ds_write_b128 v180, v[152:155] offset:27648
	s_waitcnt vmcnt(3)
	ds_write_b128 v180, v[160:163] offset:32256
	ds_write_b128 v180, v[156:159] offset:36864
	s_waitcnt vmcnt(2)
	ds_write_b128 v180, v[164:167] offset:41472
	s_waitcnt vmcnt(1)
	ds_write_b128 v180, v[168:171] offset:46080
	s_waitcnt vmcnt(0)
	ds_write_b128 v180, v[172:175] offset:50688
	s_waitcnt lgkmcnt(0)
	s_barrier
	s_cbranch_scc1 .LBB0_1375
	v_add_co_u32_e32 v128, vcc, 0x10000, v176
	global_load_dwordx4 v[136:139], v[176:177], off offset:128
	s_nop 0
	v_addc_co_u32_e32 v129, vcc, 0, v177, vcc
	v_add_co_u32_e32 v132, vcc, 0x20000, v176
	s_nop 1
	v_addc_co_u32_e32 v133, vcc, 0, v177, vcc
	v_add_co_u32_e32 v140, vcc, 0x30000, v176
	global_load_dwordx4 v[128:131], v[128:129], off offset:128
	s_nop 0
	global_load_dwordx4 v[132:135], v[132:133], off offset:128
	v_addc_co_u32_e32 v141, vcc, 0, v177, vcc
	v_add_co_u32_e32 v144, vcc, 0x40000, v176
	s_nop 1
	v_addc_co_u32_e32 v145, vcc, 0, v177, vcc
	v_add_co_u32_e32 v148, vcc, 0x50000, v176
	global_load_dwordx4 v[140:143], v[140:141], off offset:128
	s_nop 0
	global_load_dwordx4 v[144:147], v[144:145], off offset:128
	v_addc_co_u32_e32 v149, vcc, 0, v177, vcc
	v_add_co_u32_e32 v152, vcc, 0x60000, v176
	s_nop 1
	v_addc_co_u32_e32 v153, vcc, 0, v177, vcc
	v_add_co_u32_e32 v156, vcc, 0x70000, v176
	global_load_dwordx4 v[148:151], v[148:149], off offset:128
	s_nop 0
	global_load_dwordx4 v[152:155], v[152:153], off offset:128
	v_addc_co_u32_e32 v157, vcc, 0, v177, vcc
	v_add_co_u32_e32 v164, vcc, s35, v178
	global_load_dwordx4 v[160:163], v[156:157], off offset:128
	s_nop 0
	global_load_dwordx4 v[156:159], v[178:179], off offset:128
	v_addc_co_u32_e32 v165, vcc, 0, v179, vcc
	v_add_co_u32_e32 v168, vcc, s33, v178
	v_lshl_add_u64 v[176:177], v[176:177], 0, s[82:83]
	s_nop 0
	v_addc_co_u32_e32 v169, vcc, 0, v179, vcc
	v_add_co_u32_e32 v172, vcc, s40, v178
	global_load_dwordx4 v[164:167], v[164:165], off offset:128
	s_nop 0
	global_load_dwordx4 v[168:171], v[168:169], off offset:128
	v_addc_co_u32_e32 v173, vcc, 0, v179, vcc
	global_load_dwordx4 v[172:175], v[172:173], off offset:128
	v_lshl_add_u64 v[178:179], v[178:179], 0, s[82:83]
	s_branch .LBB0_1375

; __global__ void __launch_bounds__(NT, 2) mega(Params p) {
;   __shared__ __attribute__((aligned(16))) unsigned char smem[SM_TOTAL];
	.amdhsa_kernel _Z4mega6Params
		.amdhsa_group_segment_fixed_size 70676
		.amdhsa_private_segment_fixed_size 0
		.amdhsa_kernarg_size 496
		.amdhsa_user_sgpr_count 2
		.amdhsa_user_sgpr_dispatch_ptr 0
		.amdhsa_user_sgpr_queue_ptr 0
		.amdhsa_user_sgpr_kernarg_segment_ptr 1
		.amdhsa_user_sgpr_dispatch_id 0
		.amdhsa_user_sgpr_kernarg_preload_length 0
		.amdhsa_user_sgpr_kernarg_preload_offset 0
		.amdhsa_user_sgpr_private_segment_size 0
		.amdhsa_uses_dynamic_stack 0
		.amdhsa_enable_private_segment 0
		.amdhsa_system_sgpr_workgroup_id_x 1
		.amdhsa_system_sgpr_workgroup_id_y 0
		.amdhsa_system_sgpr_workgroup_id_z 0
		.amdhsa_system_sgpr_workgroup_info 0
		.amdhsa_system_vgpr_workitem_id 2
		.amdhsa_next_free_vgpr 256
		.amdhsa_next_free_sgpr 100
		.amdhsa_accum_offset 256
		.amdhsa_reserve_vcc 1
		.amdhsa_float_round_mode_32 0
		.amdhsa_float_round_mode_16_64 0
		.amdhsa_float_denorm_mode_32 3
		.amdhsa_float_denorm_mode_16_64 3
		.amdhsa_dx10_clamp 1
		.amdhsa_ieee_mode 1
		.amdhsa_fp16_overflow 0
		.amdhsa_tg_split 0
		.amdhsa_exception_fp_ieee_invalid_op 0
		.amdhsa_exception_fp_denorm_src 0
		.amdhsa_exception_fp_ieee_div_zero 0
		.amdhsa_exception_fp_ieee_overflow 0
		.amdhsa_exception_fp_ieee_underflow 0
		.amdhsa_exception_fp_ieee_inexact 0
		.amdhsa_exception_int_div_zero 0
	.end_amdhsa_kernel

; __global__ void __launch_bounds__(NT, 2) mega(Params p) {
;   __shared__ __attribute__((aligned(16))) unsigned char smem[SM_TOTAL];
;   cg::grid_group grid = cg::this_grid();
;   __shared__ uint4 xb_words;
amdhsa.kernels:
  - .agpr_count:     0
    .args:
      - .offset:         0
        .size:           240
        .value_kind:     by_value
      - .offset:         240
        .size:           4
        .value_kind:     hidden_block_count_x
      - .offset:         244
        .size:           4
        .value_kind:     hidden_block_count_y
      - .offset:         248
        .size:           4
        .value_kind:     hidden_block_count_z
      - .offset:         252
        .size:           2
        .value_kind:     hidden_group_size_x
      - .offset:         254
        .size:           2
        .value_kind:     hidden_group_size_y
      - .offset:         256
        .size:           2
        .value_kind:     hidden_group_size_z
      - .offset:         258
        .size:           2
        .value_kind:     hidden_remainder_x
      - .offset:         260
        .size:           2
        .value_kind:     hidden_remainder_y
      - .offset:         262
        .size:           2
        .value_kind:     hidden_remainder_z
      - .offset:         280
        .size:           8
        .value_kind:     hidden_global_offset_x
      - .offset:         288
        .size:           8
        .value_kind:     hidden_global_offset_y
      - .offset:         296
        .size:           8
        .value_kind:     hidden_global_offset_z
      - .offset:         304
        .size:           2
        .value_kind:     hidden_grid_dims
      - .offset:         328
        .size:           8
        .value_kind:     hidden_multigrid_sync_arg
    .group_segment_fixed_size: 70676
    .kernarg_segment_align: 8
    .kernarg_segment_size: 496
    .language:       OpenCL C
    .language_version:
      - 2
      - 0
    .max_flat_workgroup_size: 256
    .name:           _Z4mega6Params
    .private_segment_fixed_size: 0
    .sgpr_count:     106
    .sgpr_spill_count: 96
    .symbol:         _Z4mega6Params.kd
    .uniform_work_group_size: 1
    .uses_dynamic_stack: false
    .vgpr_count:     256
    .vgpr_spill_count: 0
    .wavefront_size: 64
